# sub-phase order diversity in P3: workgroups with blockIdx bit 3 run the state scan after their attention units instead of before
# speedup vs baseline: 1.0056x; 1.0056x over previous
.LBB0_515:
	s_cmp_lt_i32 s86, 4
	s_cselect_b64 s[0:1], -1, 0
	s_cmp_gt_i32 s87, 3
	s_cselect_b64 s[2:3], -1, 0
	s_and_b64 s[0:1], s[0:1], s[2:3]
	s_andn2_b64 vcc, exec, s[0:1]
	s_cbranch_vccnz .LBB0_932
	s_mov_b32 s94, 2
	s_bitcmp1_b32 s33, 3
	s_cbranch_scc0 .Lmy_p3_f
	s_mov_b32 s94, 0
.Lmy_p3_f:
	v_readfirstlane_b32 s11, v158
	v_lshrrev_b32_e32 v145, 3, v158
	s_cmp_gt_i32 s33, 31
	v_lshlrev_b32_e32 v136, 2, v158
	s_cbranch_scc1 .LBB0_540
	s_ashr_i32 s38, s33, 31
	s_lshr_b32 s0, s38, 28
	s_add_i32 s0, s33, s0
	s_and_b32 s1, s0, 0xfff0
	s_sub_i32 s1, s33, s1
	s_bfe_i32 s2, s1, 0x80000
	s_bfe_u32 s2, s2, 0x3000c
	s_add_i32 s2, s1, s2
	s_bfe_i32 s3, s2, 0x80000
	s_and_b32 s2, s2, 0xf8
	s_sub_i32 s1, s1, s2
	s_bfe_i32 s4, s1, 0x80000
	s_sext_i32_i16 s1, s4
	s_cmp_gt_i32 s1, -1
	s_sext_i32_i16 s5, s3
	s_cbranch_scc0 .LBB0_519
	s_lshl_b32 s1, s4, 1
	s_ashr_i32 s0, s0, 4
	s_lshr_b32 s2, s5, 3
	s_cbranch_execz .LBB0_520
	s_branch .LBB0_521

.LBB0_540:
	v_lshrrev_b32_e32 v147, 6, v158
	s_cmp_eq_u32 s94, 0
	s_cbranch_scc1 .Lmy_p3_attn
	v_lshl_add_u32 v2, s33, 3, v147
	s_movk_i32 s0, 0x800
	v_cmp_gt_i32_e32 vcc, s0, v2
	s_and_saveexec_b64 s[0:1], vcc
	s_cbranch_execz .LBB0_543
	s_add_u32 s2, s84, 0xf400000
	s_addc_u32 s3, s85, 0
	s_add_u32 s4, s84, 0x5099000
	v_lshlrev_b32_e32 v0, 8, v147
	s_addc_u32 s5, s85, 0
	s_lshl_b32 s8, s88, 3
	s_waitcnt lgkmcnt(0)
	v_and_b32_e32 v3, 0xfc, v136
	v_lshl_add_u32 v4, s33, 11, v0
	s_lshl_b32 s9, s88, 11
	s_mov_b64 s[6:7], 0
	s_movk_i32 s10, 0x1f00
	s_movk_i32 s11, 0xff00
	v_mov_b32_e32 v1, 0
	s_movk_i32 s12, 0x7ff

.LBB0_543:
	s_or_b64 exec, exec, s[0:1]
	s_cmp_eq_u32 s94, 1
	s_cbranch_scc1 .Lmy_p3_done
.Lmy_p3_attn:
	s_add_u32 s38, s84, 0x5903800
	s_addc_u32 s39, s85, 0
	s_getreg_b32 s54, hwreg(HW_REG_XCC_ID, 0, 4)
	s_waitcnt vmcnt(0) lgkmcnt(0)
	s_barrier
	s_mov_b64 s[2:3], exec
	v_readlane_b32 s0, v252, 5
	v_readlane_b32 s1, v252, 6
	s_and_b64 s[0:1], s[2:3], s[0:1]
	s_mov_b64 exec, s[0:1]
	s_cbranch_execz .LBB0_591
	s_mov_b64 s[4:5], exec
	v_mbcnt_lo_u32_b32 v0, s4, 0
	v_mbcnt_hi_u32_b32 v0, s5, v0
	s_and_b32 s14, s54, 7
	v_cmp_eq_u32_e32 vcc, 0, v0
	s_and_saveexec_b64 s[0:1], vcc
	s_cbranch_execz .LBB0_546
	s_lshl_b32 s6, s14, 8
	s_bcnt1_i32_b64 s4, s[4:5]
	v_mov_b32_e32 v1, s6
	v_mov_b32_e32 v2, s4
	global_atomic_add v1, v1, v2, s[38:39] sc0

.LBB0_878:
	s_cmp_eq_u32 s94, 0
	s_cbranch_scc0 .Lmy_p3_done
	s_mov_b32 s94, 1
	s_mov_b64 exec, -1
	v_lshlrev_b32_e32 v136, 2, v158
	s_branch .LBB0_540
